# single-hop barrier release: globally-last XCD leader bumps TOPGEN and all 16 per-XCC release words itself; leaders no longer do their own XGEN add (one poll hop instead of two for 7/8 XCDs)
# speedup vs baseline: 1.0153x; 1.0030x over previous
.Lxb_last_0:
	s_mov_b64 exec, s[6:7]
	v_mov_b32_e32 v2, 1
	global_atomic_add v[0:1], v2, off
	s_add_u32 s98, s22, 0x2cba400
	s_addc_u32 s99, s23, 0
	v_mov_b32_e32 v3, 0
	global_atomic_add v3, v2, s[98:99]
	global_atomic_add v3, v2, s[98:99] offset:256
	global_atomic_add v3, v2, s[98:99] offset:512
	global_atomic_add v3, v2, s[98:99] offset:768
	global_atomic_add v3, v2, s[98:99] offset:1024
	global_atomic_add v3, v2, s[98:99] offset:1280
	global_atomic_add v3, v2, s[98:99] offset:1536
	global_atomic_add v3, v2, s[98:99] offset:1792
	global_atomic_add v3, v2, s[98:99] offset:2048
	global_atomic_add v3, v2, s[98:99] offset:2304
	global_atomic_add v3, v2, s[98:99] offset:2560
	global_atomic_add v3, v2, s[98:99] offset:2816
	global_atomic_add v3, v2, s[98:99] offset:3072
	global_atomic_add v3, v2, s[98:99] offset:3328
	global_atomic_add v3, v2, s[98:99] offset:3584
	global_atomic_add v3, v2, s[98:99] offset:3840
	s_branch .LBB0_210

.LBB0_210:
	s_or_b64 exec, exec, s[6:7]
	s_mov_b64 s[6:7], exec
	v_mbcnt_lo_u32_b32 v0, s6, 0
	v_mbcnt_hi_u32_b32 v0, s7, v0
	v_cmp_eq_u32_e32 vcc, 0, v0
	s_waitcnt vmcnt(0)
	s_and_saveexec_b64 s[8:9], vcc
	s_cbranch_execz .LBB0_212
	s_bcnt1_i32_b64 s6, s[6:7]
	v_mov_b32_e32 v0, 0x2000
	v_mov_b32_e32 v1, s6
.LBB0_212:
	s_or_b64 exec, exec, s[8:9]
	s_waitcnt vmcnt(0)

.LBB0_349:
	s_or_b64 exec, exec, s[6:7]
	s_mov_b64 s[6:7], exec
	v_mbcnt_lo_u32_b32 v0, s6, 0
	v_mbcnt_hi_u32_b32 v0, s7, v0
	v_cmp_eq_u32_e32 vcc, 0, v0
	s_waitcnt vmcnt(0)
	s_and_saveexec_b64 s[8:9], vcc
	s_cbranch_execz .LBB0_351
	s_bcnt1_i32_b64 s6, s[6:7]
	v_mov_b32_e32 v0, 0x2000
	v_mov_b32_e32 v1, s6
.LBB0_351:
	s_or_b64 exec, exec, s[8:9]
	s_waitcnt vmcnt(0)

.LBB0_488:
	s_or_b64 exec, exec, s[6:7]
	s_mov_b64 s[6:7], exec
	v_mbcnt_lo_u32_b32 v0, s6, 0
	v_mbcnt_hi_u32_b32 v0, s7, v0
	v_cmp_eq_u32_e32 vcc, 0, v0
	s_waitcnt vmcnt(0)
	s_and_saveexec_b64 s[8:9], vcc
	s_cbranch_execz .LBB0_490
	s_bcnt1_i32_b64 s6, s[6:7]
	v_mov_b32_e32 v0, 0x2000
	v_mov_b32_e32 v1, s6
.LBB0_490:
	s_or_b64 exec, exec, s[8:9]
	s_waitcnt vmcnt(0)

.LBB0_895:
	s_or_b64 exec, exec, s[6:7]
	s_mov_b64 s[6:7], exec
	v_mbcnt_lo_u32_b32 v0, s6, 0
	v_mbcnt_hi_u32_b32 v0, s7, v0
	v_cmp_eq_u32_e32 vcc, 0, v0
	s_waitcnt vmcnt(0)
	s_and_saveexec_b64 s[8:9], vcc
	s_cbranch_execz .LBB0_897
	s_bcnt1_i32_b64 s6, s[6:7]
	v_mov_b32_e32 v0, 0x2000
	v_mov_b32_e32 v1, s6
.LBB0_897:
	s_or_b64 exec, exec, s[8:9]
	s_waitcnt vmcnt(0)

.Lxb_last_4:
	s_mov_b64 exec, s[8:9]
	v_mov_b32_e32 v2, 1
	global_atomic_add v[0:1], v2, off
	s_add_u32 s98, s22, 0x2cba400
	s_addc_u32 s99, s23, 0
	v_mov_b32_e32 v3, 0
	global_atomic_add v3, v2, s[98:99]
	global_atomic_add v3, v2, s[98:99] offset:256
	global_atomic_add v3, v2, s[98:99] offset:512
	global_atomic_add v3, v2, s[98:99] offset:768
	global_atomic_add v3, v2, s[98:99] offset:1024
	global_atomic_add v3, v2, s[98:99] offset:1280
	global_atomic_add v3, v2, s[98:99] offset:1536
	global_atomic_add v3, v2, s[98:99] offset:1792
	global_atomic_add v3, v2, s[98:99] offset:2048
	global_atomic_add v3, v2, s[98:99] offset:2304
	global_atomic_add v3, v2, s[98:99] offset:2560
	global_atomic_add v3, v2, s[98:99] offset:2816
	global_atomic_add v3, v2, s[98:99] offset:3072
	global_atomic_add v3, v2, s[98:99] offset:3328
	global_atomic_add v3, v2, s[98:99] offset:3584
	global_atomic_add v3, v2, s[98:99] offset:3840
	s_branch .LBB0_995

.LBB0_995:
	s_or_b64 exec, exec, s[8:9]
	s_mov_b64 s[8:9], exec
	v_mbcnt_lo_u32_b32 v0, s8, 0
	v_mbcnt_hi_u32_b32 v0, s9, v0
	v_cmp_eq_u32_e32 vcc, 0, v0
	s_waitcnt vmcnt(0)
	s_and_saveexec_b64 s[10:11], vcc
	s_cbranch_execz .LBB0_997
	s_bcnt1_i32_b64 s8, s[8:9]
	v_mov_b32_e32 v0, 0x2000
	v_mov_b32_e32 v1, s8
.LBB0_997:
	s_or_b64 exec, exec, s[10:11]
	s_waitcnt vmcnt(0)

.LBB0_1072:
	s_or_b64 exec, exec, s[8:9]
	s_mov_b64 s[8:9], exec
	v_mbcnt_lo_u32_b32 v0, s8, 0
	v_mbcnt_hi_u32_b32 v0, s9, v0
	v_cmp_eq_u32_e32 vcc, 0, v0
	s_waitcnt vmcnt(0)
	s_and_saveexec_b64 s[10:11], vcc
	s_cbranch_execz .LBB0_1074
	s_bcnt1_i32_b64 s8, s[8:9]
	v_mov_b32_e32 v0, 0x2000
	v_mov_b32_e32 v1, s8
.LBB0_1074:
	s_or_b64 exec, exec, s[10:11]
	s_waitcnt vmcnt(0)

.LBB0_1147:
	s_or_b64 exec, exec, s[8:9]
	s_mov_b64 s[8:9], exec
	v_mbcnt_lo_u32_b32 v0, s8, 0
	v_mbcnt_hi_u32_b32 v0, s9, v0
	v_cmp_eq_u32_e32 vcc, 0, v0
	s_waitcnt vmcnt(0)
	s_and_saveexec_b64 s[10:11], vcc
	s_cbranch_execz .LBB0_1149
	s_bcnt1_i32_b64 s8, s[8:9]
	v_mov_b32_e32 v0, 0x2000
	v_mov_b32_e32 v1, s8
.LBB0_1149:
	s_or_b64 exec, exec, s[10:11]
	s_waitcnt vmcnt(0)

.LBB0_1232:
	s_or_b64 exec, exec, s[8:9]
	s_mov_b64 s[8:9], exec
	v_mbcnt_lo_u32_b32 v0, s8, 0
	v_mbcnt_hi_u32_b32 v0, s9, v0
	v_cmp_eq_u32_e32 vcc, 0, v0
	s_waitcnt vmcnt(0)
	s_and_saveexec_b64 s[10:11], vcc
	s_cbranch_execz .LBB0_1234
	s_bcnt1_i32_b64 s8, s[8:9]
	v_mov_b32_e32 v0, 0x2000
	v_mov_b32_e32 v1, s8
.LBB0_1234:
	s_or_b64 exec, exec, s[10:11]
	s_waitcnt vmcnt(0)

.LBB0_1299:
	s_or_b64 exec, exec, s[8:9]
	s_mov_b64 s[8:9], exec
	v_mbcnt_lo_u32_b32 v0, s8, 0
	v_mbcnt_hi_u32_b32 v0, s9, v0
	v_cmp_eq_u32_e32 vcc, 0, v0
	s_waitcnt vmcnt(0)
	s_and_saveexec_b64 s[10:11], vcc
	s_cbranch_execz .LBB0_1301
	s_bcnt1_i32_b64 s8, s[8:9]
	v_mov_b32_e32 v0, 0x2000
	v_mov_b32_e32 v1, s8
.LBB0_1301:
	s_or_b64 exec, exec, s[10:11]
	s_waitcnt vmcnt(0)

.LBB0_1378:
	s_or_b64 exec, exec, s[6:7]
	s_mov_b64 s[6:7], exec
	v_mbcnt_lo_u32_b32 v0, s6, 0
	v_mbcnt_hi_u32_b32 v0, s7, v0
	v_cmp_eq_u32_e32 vcc, 0, v0
	s_waitcnt vmcnt(0)
	s_and_saveexec_b64 s[8:9], vcc
	s_cbranch_execz .LBB0_1380
	s_bcnt1_i32_b64 s6, s[6:7]
	v_mov_b32_e32 v0, 0x2000
	v_mov_b32_e32 v1, s6
.LBB0_1380:
	s_or_b64 exec, exec, s[8:9]
	s_waitcnt vmcnt(0)
